# prompt DSA PV moved to matrix cores: P^T x V via mfma_f32_16x16x32_f16 with f32 accumulation (was packed-f16 VALU FMAs), fp8 V bytes converted exactly to f16, no transpose needed
# speedup vs baseline: 1.0218x; 1.0218x over previous
; __device__ __forceinline__ void dsa_unit(int wv, const Args& A, LAS unsigned char* lds, int s, int qt) {
;     ...
;         { const int ksub = lane >> 4, sl16 = lane & 15, g = sl16 >> 3;
;             float acc[4][16];
; #pragma unroll
;             for (int hh = 0; hh < 4; ++hh)
; #pragma unroll
;                 for (int d = 0; d < 16; ++d) acc[hh][d] = 0.f;
;             for (int eb = 0; eb < n; eb += 64) {
;                 h16x2 a2[4][8];
; #pragma unroll
;                 for (int hh = 0; hh < 4; ++hh)
; #pragma unroll
;                     for (int d2 = 0; d2 < 8; ++d2) a2[hh][d2] = (h16x2){0, 0};
; #pragma unroll
;                 for (int e0 = 0; e0 < 64; e0 += 4) { const int e = eb + e0 + ksub; const int j_ = lst[e];
;                     const unsigned char* vp = (s < 2) ? ws + WS_VC8 + ((size_t)s * SEQ + j_) * 256 : (j_ < PAST ? ws + WS_CV8 + ((size_t)(s - 2) * PAST + j_) * 256 : ws + WS_VC8 + ((size_t)NP + (s - 2) * 64 + (j_ - PAST)) * 256);
;                     const u32x4 wv8 = *(const u32x4*)(vp + sl16 * 16);
.LBB0_1471:
	s_mov_b32 s12, 0
	v_mov_b32_e32 v28, 0
	v_mov_b32_e32 v29, 0
	v_mov_b32_e32 v30, 0
	v_mov_b32_e32 v31, 0
	v_mov_b32_e32 v32, 0
	v_mov_b32_e32 v33, 0
	v_mov_b32_e32 v34, 0
	v_mov_b32_e32 v35, 0
	v_mov_b32_e32 v36, 0
	v_mov_b32_e32 v37, 0
	v_mov_b32_e32 v38, 0
	v_mov_b32_e32 v39, 0
	v_mov_b32_e32 v40, 0
	v_mov_b32_e32 v41, 0
	v_mov_b32_e32 v42, 0
	v_mov_b32_e32 v43, 0
	v_mov_b32_e32 v44, 0
	v_mov_b32_e32 v45, 0
	v_mov_b32_e32 v46, 0
	v_mov_b32_e32 v47, 0
	v_mov_b32_e32 v48, 0
	v_mov_b32_e32 v49, 0
	v_mov_b32_e32 v50, 0
	v_mov_b32_e32 v51, 0
	v_mov_b32_e32 v52, 0
	v_mov_b32_e32 v53, 0
	v_mov_b32_e32 v54, 0
	v_mov_b32_e32 v55, 0
	v_mov_b32_e32 v56, 0
	v_mov_b32_e32 v57, 0
	v_mov_b32_e32 v58, 0
	v_mov_b32_e32 v59, 0
	v_mov_b32_e32 v60, 0
	v_mov_b32_e32 v61, 0
	v_mov_b32_e32 v62, 0
	v_mov_b32_e32 v63, 0
	v_mov_b32_e32 v64, 0
	v_mov_b32_e32 v65, 0
	v_mov_b32_e32 v66, 0
	v_mov_b32_e32 v67, 0
	v_mov_b32_e32 v68, 0
	v_mov_b32_e32 v69, 0
	v_mov_b32_e32 v70, 0
	v_mov_b32_e32 v71, 0
	v_mov_b32_e32 v72, 0
	v_mov_b32_e32 v73, 0
	v_mov_b32_e32 v74, 0
	v_mov_b32_e32 v75, 0
	v_mov_b32_e32 v76, 0
	v_mov_b32_e32 v77, 0
	v_mov_b32_e32 v78, 0
	v_mov_b32_e32 v79, 0
	v_mov_b32_e32 v80, 0
	v_mov_b32_e32 v81, 0
	v_mov_b32_e32 v82, 0
	v_mov_b32_e32 v83, 0
	v_mov_b32_e32 v84, 0
	v_mov_b32_e32 v85, 0
	v_mov_b32_e32 v86, 0
	v_mov_b32_e32 v87, 0
	v_mov_b32_e32 v88, 0
	v_mov_b32_e32 v89, 0
	v_mov_b32_e32 v90, 0
	v_mov_b32_e32 v91, 0
	v_mov_b32_e32 v2, 0
	v_mov_b32_e32 v3, 0
	v_mov_b32_e32 v4, 0
	v_mov_b32_e32 v5, 0
	v_mov_b32_e32 v6, 0
	v_mov_b32_e32 v7, 0
	v_mov_b32_e32 v8, 0
	v_mov_b32_e32 v9, 0
	v_mbcnt_lo_u32_b32 v169, -1, 0
	v_mbcnt_hi_u32_b32 v169, -1, v169
	v_lshrrev_b32_e32 v92, 4, v169
	v_and_b32_e32 v169, 15, v169
	v_lshlrev_b32_e32 v92, 4, v92
	v_lshl_add_u32 v92, v169, 1, v92
	v_add_u32_e32 v92, s28, v92
	v_lshlrev_b32_e32 v169, 4, v169
	v_add_u32_e32 v168, s0, v105
	v_add_u32_e32 v168, 0x13000, v168
	ds_read_u16 v136, v168
	ds_read_u16 v137, v168 offset:8
	ds_read_u16 v138, v168 offset:16
	ds_read_u16 v139, v168 offset:24
	ds_read_u16 v140, v168 offset:32
	ds_read_u16 v141, v168 offset:40
	ds_read_u16 v142, v168 offset:48
	ds_read_u16 v143, v168 offset:56
	ds_read_u16 v144, v168 offset:64
	ds_read_u16 v145, v168 offset:72
	ds_read_u16 v146, v168 offset:80
	ds_read_u16 v147, v168 offset:88
	ds_read_u16 v148, v168 offset:96
	ds_read_u16 v149, v168 offset:104
	ds_read_u16 v178, v168 offset:112
	ds_read_u16 v179, v168 offset:120
	s_waitcnt lgkmcnt(0)
	v_add_lshl_u32 v136, s48, v136, 8
	v_add_u32_e32 v136, v169, v136
	v_add_lshl_u32 v137, s48, v137, 8
	v_add_u32_e32 v137, v169, v137
	v_add_lshl_u32 v138, s48, v138, 8
	v_add_u32_e32 v138, v169, v138
	v_add_lshl_u32 v139, s48, v139, 8
	v_add_u32_e32 v139, v169, v139
	v_add_lshl_u32 v140, s48, v140, 8
	v_add_u32_e32 v140, v169, v140
	v_add_lshl_u32 v141, s48, v141, 8
	v_add_u32_e32 v141, v169, v141
	v_add_lshl_u32 v142, s48, v142, 8
	v_add_u32_e32 v142, v169, v142
	v_add_lshl_u32 v143, s48, v143, 8
	v_add_u32_e32 v143, v169, v143
	v_add_lshl_u32 v144, s48, v144, 8
	v_add_u32_e32 v144, v169, v144
	v_add_lshl_u32 v145, s48, v145, 8
	v_add_u32_e32 v145, v169, v145
	v_add_lshl_u32 v146, s48, v146, 8
	v_add_u32_e32 v146, v169, v146
	v_add_lshl_u32 v147, s48, v147, 8
	v_add_u32_e32 v147, v169, v147
	v_add_lshl_u32 v148, s48, v148, 8
	v_add_u32_e32 v148, v169, v148
	v_add_lshl_u32 v149, s48, v149, 8
	v_add_u32_e32 v149, v169, v149
	v_add_lshl_u32 v178, s48, v178, 8
	v_add_u32_e32 v178, v169, v178
	v_add_lshl_u32 v179, s48, v179, 8
	v_add_u32_e32 v179, v169, v179
	global_load_dwordx4 v[160:163], v136, s[86:87]
	global_load_dwordx4 v[164:167], v137, s[86:87]
	global_load_dwordx4 v[180:183], v138, s[86:87]
	global_load_dwordx4 v[184:187], v139, s[86:87]
	global_load_dwordx4 v[188:191], v140, s[86:87]
	global_load_dwordx4 v[192:195], v141, s[86:87]
	global_load_dwordx4 v[196:199], v142, s[86:87]
	global_load_dwordx4 v[200:203], v143, s[86:87]
	global_load_dwordx4 v[204:207], v144, s[86:87]
	global_load_dwordx4 v[208:211], v145, s[86:87]
	global_load_dwordx4 v[212:215], v146, s[86:87]
	global_load_dwordx4 v[216:219], v147, s[86:87]
	global_load_dwordx4 v[220:223], v148, s[86:87]
	global_load_dwordx4 v[224:227], v149, s[86:87]
	global_load_dwordx4 v[228:231], v178, s[86:87]
	global_load_dwordx4 v[232:235], v179, s[86:87]
; #define LAS __attribute__((address_space(3)))
; __device__ __forceinline__ void dsa_unit(int wv, const Args& A, LAS unsigned char* lds, int s, int qt) {
;     ...
;             for (int eb = 0; eb < n; eb += 64) {
;                 h16x2 a2[4][8];
; #pragma unroll
;                 for (int hh = 0; hh < 4; ++hh)
; #pragma unroll
;                     for (int d2 = 0; d2 < 8; ++d2) a2[hh][d2] = (h16x2){0, 0};
; #pragma unroll
;                 for (int e0 = 0; e0 < 64; e0 += 4) { const int e = eb + e0 + ksub; const int j_ = lst[e];
;                     const unsigned char* vp = (s < 2) ? ws + WS_VC8 + ((size_t)s * SEQ + j_) * 256 : (j_ < PAST ? ws + WS_CV8 + ((size_t)(s - 2) * PAST + j_) * 256 : ws + WS_VC8 + ((size_t)NP + (s - 2) * 64 + (j_ - PAST)) * 256);
;                     const u32x4 wv8 = *(const u32x4*)(vp + sl16 * 16);
;                     const h16x4 ph = *(const LAS h16x4*)(Pw + e * 8 + g * 4);
;                     h16x2 v2[8];
; #pragma unroll
;                     for (int d2 = 0; d2 < 8; ++d2) { const f32x2 f2 = (d2 & 1) ? __builtin_amdgcn_cvt_pk_f32_fp8((int)wv8[d2 >> 1], true) : __builtin_amdgcn_cvt_pk_f32_fp8((int)wv8[d2 >> 1], false);
;                         v2[d2] = (h16x2){(h16)f2[0], (h16)f2[1]}; }
; #pragma unroll
;                     for (int hh = 0; hh < 4; ++hh) { const h16x2 pp = {ph[hh], ph[hh]};
; #pragma unroll
;                         for (int d2 = 0; d2 < 8; ++d2) a2[hh][d2] = __builtin_elementwise_fma(pp, v2[d2], a2[hh][d2]); } }
; #pragma unroll
;                 for (int hh = 0; hh < 4; ++hh)
; #pragma unroll
;                     for (int d2 = 0; d2 < 8; ++d2) { acc[hh][2 * d2] += (float)a2[hh][d2][0]; acc[hh][2 * d2 + 1] += (float)a2[hh][d2][1]; }
.LBB0_1472:
	s_add_i32 s12, s12, 64
	s_cmp_ge_i32 s12, s29
	s_cselect_b32 s98, 0, 0x80
	v_add_u32_e32 v168, s98, v168
	ds_read_u16 v136, v168
	ds_read_u16 v137, v168 offset:8
	ds_read_u16 v138, v168 offset:16
	ds_read_u16 v139, v168 offset:24
	ds_read_u16 v140, v168 offset:32
	ds_read_u16 v141, v168 offset:40
	ds_read_u16 v142, v168 offset:48
	ds_read_u16 v143, v168 offset:56
	ds_read_u16 v144, v168 offset:64
	ds_read_u16 v145, v168 offset:72
	ds_read_u16 v146, v168 offset:80
	ds_read_u16 v147, v168 offset:88
	ds_read_u16 v148, v168 offset:96
	ds_read_u16 v149, v168 offset:104
	ds_read_u16 v178, v168 offset:112
	ds_read_u16 v179, v168 offset:120
	s_mov_b64 exec, s[8:9]
	ds_read_u16 v248, v92
	ds_read_u16 v249, v92 offset:64
	ds_read_u16 v250, v92 offset:128
	ds_read_u16 v251, v92 offset:192
	ds_read_u16 v252, v92 offset:256
	ds_read_u16 v253, v92 offset:320
	ds_read_u16 v254, v92 offset:384
	ds_read_u16 v255, v92 offset:448
	s_mov_b64 exec, -1
	s_waitcnt vmcnt(14)
	v_cvt_pk_f32_fp8_e32 v[10:11], v160
	v_cvt_pk_f32_fp8_sdwa v[12:13], v160 src0_sel:WORD_1
	v_cvt_pk_f32_fp8_e32 v[14:15], v161
	v_cvt_pk_f32_fp8_sdwa v[16:17], v161 src0_sel:WORD_1
	v_cvt_pk_f32_fp8_e32 v[18:19], v164
	v_cvt_pk_f32_fp8_sdwa v[20:21], v164 src0_sel:WORD_1
	v_cvt_pk_f32_fp8_e32 v[108:109], v165
	v_cvt_pk_f32_fp8_sdwa v[110:111], v165 src0_sel:WORD_1
	v_cvt_pk_f16_f32 v112, v10, v18
	v_cvt_pk_f16_f32 v116, v11, v19
	v_cvt_pk_f16_f32 v120, v12, v20
	v_cvt_pk_f16_f32 v124, v13, v21
	v_cvt_pk_f16_f32 v128, v14, v108
	v_cvt_pk_f16_f32 v132, v15, v109
	v_cvt_pk_f16_f32 v240, v16, v110
	v_cvt_pk_f16_f32 v244, v17, v111
	s_waitcnt vmcnt(12)
	v_cvt_pk_f32_fp8_e32 v[10:11], v180
	v_cvt_pk_f32_fp8_sdwa v[12:13], v180 src0_sel:WORD_1
	v_cvt_pk_f32_fp8_e32 v[14:15], v181
	v_cvt_pk_f32_fp8_sdwa v[16:17], v181 src0_sel:WORD_1
	v_cvt_pk_f32_fp8_e32 v[18:19], v184
	v_cvt_pk_f32_fp8_sdwa v[20:21], v184 src0_sel:WORD_1
	v_cvt_pk_f32_fp8_e32 v[108:109], v185
	v_cvt_pk_f32_fp8_sdwa v[110:111], v185 src0_sel:WORD_1
	v_cvt_pk_f16_f32 v113, v10, v18
	v_cvt_pk_f16_f32 v117, v11, v19
	v_cvt_pk_f16_f32 v121, v12, v20
	v_cvt_pk_f16_f32 v125, v13, v21
	v_cvt_pk_f16_f32 v129, v14, v108
	v_cvt_pk_f16_f32 v133, v15, v109
	v_cvt_pk_f16_f32 v241, v16, v110
	v_cvt_pk_f16_f32 v245, v17, v111
	s_waitcnt vmcnt(10)
	v_cvt_pk_f32_fp8_e32 v[10:11], v188
	v_cvt_pk_f32_fp8_sdwa v[12:13], v188 src0_sel:WORD_1
	v_cvt_pk_f32_fp8_e32 v[14:15], v189
	v_cvt_pk_f32_fp8_sdwa v[16:17], v189 src0_sel:WORD_1
	v_cvt_pk_f32_fp8_e32 v[18:19], v192
	v_cvt_pk_f32_fp8_sdwa v[20:21], v192 src0_sel:WORD_1
	v_cvt_pk_f32_fp8_e32 v[108:109], v193
	v_cvt_pk_f32_fp8_sdwa v[110:111], v193 src0_sel:WORD_1
	v_cvt_pk_f16_f32 v114, v10, v18
	v_cvt_pk_f16_f32 v118, v11, v19
	v_cvt_pk_f16_f32 v122, v12, v20
	v_cvt_pk_f16_f32 v126, v13, v21
	v_cvt_pk_f16_f32 v130, v14, v108
	v_cvt_pk_f16_f32 v134, v15, v109
	v_cvt_pk_f16_f32 v242, v16, v110
	v_cvt_pk_f16_f32 v246, v17, v111
	s_waitcnt vmcnt(8)
	v_cvt_pk_f32_fp8_e32 v[10:11], v196
	v_cvt_pk_f32_fp8_sdwa v[12:13], v196 src0_sel:WORD_1
	v_cvt_pk_f32_fp8_e32 v[14:15], v197
	v_cvt_pk_f32_fp8_sdwa v[16:17], v197 src0_sel:WORD_1
	v_cvt_pk_f32_fp8_e32 v[18:19], v200
	v_cvt_pk_f32_fp8_sdwa v[20:21], v200 src0_sel:WORD_1
	v_cvt_pk_f32_fp8_e32 v[108:109], v201
	v_cvt_pk_f32_fp8_sdwa v[110:111], v201 src0_sel:WORD_1
	v_cvt_pk_f16_f32 v115, v10, v18
	v_cvt_pk_f16_f32 v119, v11, v19
	v_cvt_pk_f16_f32 v123, v12, v20
	v_cvt_pk_f16_f32 v127, v13, v21
	v_cvt_pk_f16_f32 v131, v14, v108
	v_cvt_pk_f16_f32 v135, v15, v109
	v_cvt_pk_f16_f32 v243, v16, v110
	v_cvt_pk_f16_f32 v247, v17, v111
	s_waitcnt lgkmcnt(0)
	s_mov_b64 exec, s[8:9]
	v_lshl_or_b32 v2, v249, 16, v248
	v_lshl_or_b32 v3, v251, 16, v250
	v_lshl_or_b32 v4, v253, 16, v252
	v_lshl_or_b32 v5, v255, 16, v254
	ds_read_u16 v248, v92 offset:512
	ds_read_u16 v249, v92 offset:576
	ds_read_u16 v250, v92 offset:640
	ds_read_u16 v251, v92 offset:704
	ds_read_u16 v252, v92 offset:768
	ds_read_u16 v253, v92 offset:832
	ds_read_u16 v254, v92 offset:896
	ds_read_u16 v255, v92 offset:960
	s_mov_b64 exec, -1
	s_nop 3
	v_mfma_f32_16x16x32_f16 v[28:31], v[2:5], v[112:115], v[28:31]
	v_mfma_f32_16x16x32_f16 v[32:35], v[2:5], v[116:119], v[32:35]
	v_mfma_f32_16x16x32_f16 v[36:39], v[2:5], v[120:123], v[36:39]
	v_mfma_f32_16x16x32_f16 v[40:43], v[2:5], v[124:127], v[40:43]
	v_mfma_f32_16x16x32_f16 v[44:47], v[2:5], v[128:131], v[44:47]
	v_mfma_f32_16x16x32_f16 v[48:51], v[2:5], v[132:135], v[48:51]
	v_mfma_f32_16x16x32_f16 v[52:55], v[2:5], v[240:243], v[52:55]
	v_mfma_f32_16x16x32_f16 v[56:59], v[2:5], v[244:247], v[56:59]
	v_cvt_pk_f32_fp8_e32 v[10:11], v162
	v_cvt_pk_f32_fp8_sdwa v[12:13], v162 src0_sel:WORD_1
	v_cvt_pk_f32_fp8_e32 v[14:15], v163
	v_cvt_pk_f32_fp8_sdwa v[16:17], v163 src0_sel:WORD_1
	v_add_lshl_u32 v136, s48, v136, 8
	v_add_u32_e32 v136, v169, v136
	global_load_dwordx4 v[160:163], v136, s[86:87]
	v_cvt_pk_f32_fp8_e32 v[18:19], v166
	v_cvt_pk_f32_fp8_sdwa v[20:21], v166 src0_sel:WORD_1
	v_cvt_pk_f32_fp8_e32 v[108:109], v167
	v_cvt_pk_f32_fp8_sdwa v[110:111], v167 src0_sel:WORD_1
	v_add_lshl_u32 v137, s48, v137, 8
	v_add_u32_e32 v137, v169, v137
	global_load_dwordx4 v[164:167], v137, s[86:87]
	v_cvt_pk_f16_f32 v112, v10, v18
	v_cvt_pk_f16_f32 v116, v11, v19
	v_cvt_pk_f16_f32 v120, v12, v20
	v_cvt_pk_f16_f32 v124, v13, v21
	v_cvt_pk_f16_f32 v128, v14, v108
	v_cvt_pk_f16_f32 v132, v15, v109
	v_cvt_pk_f16_f32 v240, v16, v110
	v_cvt_pk_f16_f32 v244, v17, v111
	v_cvt_pk_f32_fp8_e32 v[10:11], v182
	v_cvt_pk_f32_fp8_sdwa v[12:13], v182 src0_sel:WORD_1
	v_cvt_pk_f32_fp8_e32 v[14:15], v183
	v_cvt_pk_f32_fp8_sdwa v[16:17], v183 src0_sel:WORD_1
; #define LAS __attribute__((address_space(3)))
; __device__ __forceinline__ void dsa_unit(int wv, const Args& A, LAS unsigned char* lds, int s, int qt) {
;     ...
;             for (int eb = 0; eb < n; eb += 64) {
;                 h16x2 a2[4][8];
; #pragma unroll
;                 for (int hh = 0; hh < 4; ++hh)
; #pragma unroll
;                     for (int d2 = 0; d2 < 8; ++d2) a2[hh][d2] = (h16x2){0, 0};
; #pragma unroll
;                 for (int e0 = 0; e0 < 64; e0 += 4) { const int e = eb + e0 + ksub; const int j_ = lst[e];
;                     const unsigned char* vp = (s < 2) ? ws + WS_VC8 + ((size_t)s * SEQ + j_) * 256 : (j_ < PAST ? ws + WS_CV8 + ((size_t)(s - 2) * PAST + j_) * 256 : ws + WS_VC8 + ((size_t)NP + (s - 2) * 64 + (j_ - PAST)) * 256);
;                     const u32x4 wv8 = *(const u32x4*)(vp + sl16 * 16);
;                     const h16x4 ph = *(const LAS h16x4*)(Pw + e * 8 + g * 4);
;                     h16x2 v2[8];
; #pragma unroll
;                     for (int d2 = 0; d2 < 8; ++d2) { const f32x2 f2 = (d2 & 1) ? __builtin_amdgcn_cvt_pk_f32_fp8((int)wv8[d2 >> 1], true) : __builtin_amdgcn_cvt_pk_f32_fp8((int)wv8[d2 >> 1], false);
;                         v2[d2] = (h16x2){(h16)f2[0], (h16)f2[1]}; }
; #pragma unroll
;                     for (int hh = 0; hh < 4; ++hh) { const h16x2 pp = {ph[hh], ph[hh]};
; #pragma unroll
;                         for (int d2 = 0; d2 < 8; ++d2) a2[hh][d2] = __builtin_elementwise_fma(pp, v2[d2], a2[hh][d2]); } }
; #pragma unroll
;                 for (int hh = 0; hh < 4; ++hh)
; #pragma unroll
;                     for (int d2 = 0; d2 < 8; ++d2) { acc[hh][2 * d2] += (float)a2[hh][d2][0]; acc[hh][2 * d2 + 1] += (float)a2[hh][d2][1]; }
	v_add_lshl_u32 v138, s48, v138, 8
	v_add_u32_e32 v138, v169, v138
	global_load_dwordx4 v[180:183], v138, s[86:87]
	v_cvt_pk_f32_fp8_e32 v[18:19], v186
	v_cvt_pk_f32_fp8_sdwa v[20:21], v186 src0_sel:WORD_1
	v_cvt_pk_f32_fp8_e32 v[108:109], v187
	v_cvt_pk_f32_fp8_sdwa v[110:111], v187 src0_sel:WORD_1
	v_add_lshl_u32 v139, s48, v139, 8
	v_add_u32_e32 v139, v169, v139
	global_load_dwordx4 v[184:187], v139, s[86:87]
	v_cvt_pk_f16_f32 v113, v10, v18
	v_cvt_pk_f16_f32 v117, v11, v19
	v_cvt_pk_f16_f32 v121, v12, v20
	v_cvt_pk_f16_f32 v125, v13, v21
	v_cvt_pk_f16_f32 v129, v14, v108
	v_cvt_pk_f16_f32 v133, v15, v109
	v_cvt_pk_f16_f32 v241, v16, v110
	v_cvt_pk_f16_f32 v245, v17, v111
	v_cvt_pk_f32_fp8_e32 v[10:11], v190
	v_cvt_pk_f32_fp8_sdwa v[12:13], v190 src0_sel:WORD_1
	v_cvt_pk_f32_fp8_e32 v[14:15], v191
	v_cvt_pk_f32_fp8_sdwa v[16:17], v191 src0_sel:WORD_1
	v_add_lshl_u32 v140, s48, v140, 8
	v_add_u32_e32 v140, v169, v140
	global_load_dwordx4 v[188:191], v140, s[86:87]
	v_cvt_pk_f32_fp8_e32 v[18:19], v194
	v_cvt_pk_f32_fp8_sdwa v[20:21], v194 src0_sel:WORD_1
	v_cvt_pk_f32_fp8_e32 v[108:109], v195
	v_cvt_pk_f32_fp8_sdwa v[110:111], v195 src0_sel:WORD_1
	v_add_lshl_u32 v141, s48, v141, 8
	v_add_u32_e32 v141, v169, v141
	global_load_dwordx4 v[192:195], v141, s[86:87]
	v_cvt_pk_f16_f32 v114, v10, v18
	v_cvt_pk_f16_f32 v118, v11, v19
	v_cvt_pk_f16_f32 v122, v12, v20
	v_cvt_pk_f16_f32 v126, v13, v21
	v_cvt_pk_f16_f32 v130, v14, v108
	v_cvt_pk_f16_f32 v134, v15, v109
	v_cvt_pk_f16_f32 v242, v16, v110
	v_cvt_pk_f16_f32 v246, v17, v111
	v_cvt_pk_f32_fp8_e32 v[10:11], v198
	v_cvt_pk_f32_fp8_sdwa v[12:13], v198 src0_sel:WORD_1
	v_cvt_pk_f32_fp8_e32 v[14:15], v199
	v_cvt_pk_f32_fp8_sdwa v[16:17], v199 src0_sel:WORD_1
	v_add_lshl_u32 v142, s48, v142, 8
	v_add_u32_e32 v142, v169, v142
	global_load_dwordx4 v[196:199], v142, s[86:87]
	v_cvt_pk_f32_fp8_e32 v[18:19], v202
	v_cvt_pk_f32_fp8_sdwa v[20:21], v202 src0_sel:WORD_1
	v_cvt_pk_f32_fp8_e32 v[108:109], v203
	v_cvt_pk_f32_fp8_sdwa v[110:111], v203 src0_sel:WORD_1
	v_add_lshl_u32 v143, s48, v143, 8
	v_add_u32_e32 v143, v169, v143
	global_load_dwordx4 v[200:203], v143, s[86:87]
	v_cvt_pk_f16_f32 v115, v10, v18
	v_cvt_pk_f16_f32 v119, v11, v19
	v_cvt_pk_f16_f32 v123, v12, v20
	v_cvt_pk_f16_f32 v127, v13, v21
	v_cvt_pk_f16_f32 v131, v14, v108
	v_cvt_pk_f16_f32 v135, v15, v109
	v_cvt_pk_f16_f32 v243, v16, v110
	v_cvt_pk_f16_f32 v247, v17, v111
	v_mfma_f32_16x16x32_f16 v[60:63], v[2:5], v[112:115], v[60:63]
	v_mfma_f32_16x16x32_f16 v[64:67], v[2:5], v[116:119], v[64:67]
	v_mfma_f32_16x16x32_f16 v[68:71], v[2:5], v[120:123], v[68:71]
	v_mfma_f32_16x16x32_f16 v[72:75], v[2:5], v[124:127], v[72:75]
	v_mfma_f32_16x16x32_f16 v[76:79], v[2:5], v[128:131], v[76:79]
	v_mfma_f32_16x16x32_f16 v[80:83], v[2:5], v[132:135], v[80:83]
	v_mfma_f32_16x16x32_f16 v[84:87], v[2:5], v[240:243], v[84:87]
	v_mfma_f32_16x16x32_f16 v[88:91], v[2:5], v[244:247], v[88:91]
	s_waitcnt vmcnt(14)
	v_cvt_pk_f32_fp8_e32 v[10:11], v204
	v_cvt_pk_f32_fp8_sdwa v[12:13], v204 src0_sel:WORD_1
	v_cvt_pk_f32_fp8_e32 v[14:15], v205
	v_cvt_pk_f32_fp8_sdwa v[16:17], v205 src0_sel:WORD_1
	v_cvt_pk_f32_fp8_e32 v[18:19], v208
	v_cvt_pk_f32_fp8_sdwa v[20:21], v208 src0_sel:WORD_1
	v_cvt_pk_f32_fp8_e32 v[108:109], v209
	v_cvt_pk_f32_fp8_sdwa v[110:111], v209 src0_sel:WORD_1
	v_cvt_pk_f16_f32 v112, v10, v18
	v_cvt_pk_f16_f32 v116, v11, v19
	v_cvt_pk_f16_f32 v120, v12, v20
	v_cvt_pk_f16_f32 v124, v13, v21
	v_cvt_pk_f16_f32 v128, v14, v108
	v_cvt_pk_f16_f32 v132, v15, v109
	v_cvt_pk_f16_f32 v240, v16, v110
	v_cvt_pk_f16_f32 v244, v17, v111
	s_waitcnt vmcnt(12)
	v_cvt_pk_f32_fp8_e32 v[10:11], v212
	v_cvt_pk_f32_fp8_sdwa v[12:13], v212 src0_sel:WORD_1
	v_cvt_pk_f32_fp8_e32 v[14:15], v213
	v_cvt_pk_f32_fp8_sdwa v[16:17], v213 src0_sel:WORD_1
	v_cvt_pk_f32_fp8_e32 v[18:19], v216
	v_cvt_pk_f32_fp8_sdwa v[20:21], v216 src0_sel:WORD_1
	v_cvt_pk_f32_fp8_e32 v[108:109], v217
	v_cvt_pk_f32_fp8_sdwa v[110:111], v217 src0_sel:WORD_1
	v_cvt_pk_f16_f32 v113, v10, v18
	v_cvt_pk_f16_f32 v117, v11, v19
	v_cvt_pk_f16_f32 v121, v12, v20
	v_cvt_pk_f16_f32 v125, v13, v21
	v_cvt_pk_f16_f32 v129, v14, v108
	v_cvt_pk_f16_f32 v133, v15, v109
	v_cvt_pk_f16_f32 v241, v16, v110
	v_cvt_pk_f16_f32 v245, v17, v111
	s_waitcnt vmcnt(10)
	v_cvt_pk_f32_fp8_e32 v[10:11], v220
	v_cvt_pk_f32_fp8_sdwa v[12:13], v220 src0_sel:WORD_1
	v_cvt_pk_f32_fp8_e32 v[14:15], v221
	v_cvt_pk_f32_fp8_sdwa v[16:17], v221 src0_sel:WORD_1
	v_cvt_pk_f32_fp8_e32 v[18:19], v224
	v_cvt_pk_f32_fp8_sdwa v[20:21], v224 src0_sel:WORD_1
	v_cvt_pk_f32_fp8_e32 v[108:109], v225
	v_cvt_pk_f32_fp8_sdwa v[110:111], v225 src0_sel:WORD_1
	v_cvt_pk_f16_f32 v114, v10, v18
	v_cvt_pk_f16_f32 v118, v11, v19
	v_cvt_pk_f16_f32 v122, v12, v20
	v_cvt_pk_f16_f32 v126, v13, v21
	v_cvt_pk_f16_f32 v130, v14, v108
	v_cvt_pk_f16_f32 v134, v15, v109
	v_cvt_pk_f16_f32 v242, v16, v110
	v_cvt_pk_f16_f32 v246, v17, v111
	s_waitcnt vmcnt(8)
; #define LAS __attribute__((address_space(3)))
; __device__ __forceinline__ void dsa_unit(int wv, const Args& A, LAS unsigned char* lds, int s, int qt) {
;     ...
;             for (int eb = 0; eb < n; eb += 64) {
;                 h16x2 a2[4][8];
; #pragma unroll
;                 for (int hh = 0; hh < 4; ++hh)
; #pragma unroll
;                     for (int d2 = 0; d2 < 8; ++d2) a2[hh][d2] = (h16x2){0, 0};
; #pragma unroll
;                 for (int e0 = 0; e0 < 64; e0 += 4) { const int e = eb + e0 + ksub; const int j_ = lst[e];
;                     const unsigned char* vp = (s < 2) ? ws + WS_VC8 + ((size_t)s * SEQ + j_) * 256 : (j_ < PAST ? ws + WS_CV8 + ((size_t)(s - 2) * PAST + j_) * 256 : ws + WS_VC8 + ((size_t)NP + (s - 2) * 64 + (j_ - PAST)) * 256);
;                     const u32x4 wv8 = *(const u32x4*)(vp + sl16 * 16);
;                     const h16x4 ph = *(const LAS h16x4*)(Pw + e * 8 + g * 4);
;                     h16x2 v2[8];
; #pragma unroll
;                     for (int d2 = 0; d2 < 8; ++d2) { const f32x2 f2 = (d2 & 1) ? __builtin_amdgcn_cvt_pk_f32_fp8((int)wv8[d2 >> 1], true) : __builtin_amdgcn_cvt_pk_f32_fp8((int)wv8[d2 >> 1], false);
;                         v2[d2] = (h16x2){(h16)f2[0], (h16)f2[1]}; }
; #pragma unroll
;                     for (int hh = 0; hh < 4; ++hh) { const h16x2 pp = {ph[hh], ph[hh]};
; #pragma unroll
;                         for (int d2 = 0; d2 < 8; ++d2) a2[hh][d2] = __builtin_elementwise_fma(pp, v2[d2], a2[hh][d2]); } }
; #pragma unroll
;                 for (int hh = 0; hh < 4; ++hh)
; #pragma unroll
;                     for (int d2 = 0; d2 < 8; ++d2) { acc[hh][2 * d2] += (float)a2[hh][d2][0]; acc[hh][2 * d2 + 1] += (float)a2[hh][d2][1]; }
	v_cvt_pk_f32_fp8_e32 v[10:11], v228
	v_cvt_pk_f32_fp8_sdwa v[12:13], v228 src0_sel:WORD_1
	v_cvt_pk_f32_fp8_e32 v[14:15], v229
	v_cvt_pk_f32_fp8_sdwa v[16:17], v229 src0_sel:WORD_1
	v_cvt_pk_f32_fp8_e32 v[18:19], v232
	v_cvt_pk_f32_fp8_sdwa v[20:21], v232 src0_sel:WORD_1
	v_cvt_pk_f32_fp8_e32 v[108:109], v233
	v_cvt_pk_f32_fp8_sdwa v[110:111], v233 src0_sel:WORD_1
	v_cvt_pk_f16_f32 v115, v10, v18
	v_cvt_pk_f16_f32 v119, v11, v19
	v_cvt_pk_f16_f32 v123, v12, v20
	v_cvt_pk_f16_f32 v127, v13, v21
	v_cvt_pk_f16_f32 v131, v14, v108
	v_cvt_pk_f16_f32 v135, v15, v109
	v_cvt_pk_f16_f32 v243, v16, v110
	v_cvt_pk_f16_f32 v247, v17, v111
	s_waitcnt lgkmcnt(0)
	s_mov_b64 exec, s[8:9]
	v_lshl_or_b32 v6, v249, 16, v248
	v_lshl_or_b32 v7, v251, 16, v250
	v_lshl_or_b32 v8, v253, 16, v252
	v_lshl_or_b32 v9, v255, 16, v254
	v_add_u32_e32 v92, 0x400, v92
	s_mov_b64 exec, -1
	s_nop 3
	v_mfma_f32_16x16x32_f16 v[28:31], v[6:9], v[112:115], v[28:31]
	v_mfma_f32_16x16x32_f16 v[32:35], v[6:9], v[116:119], v[32:35]
	v_mfma_f32_16x16x32_f16 v[36:39], v[6:9], v[120:123], v[36:39]
	v_mfma_f32_16x16x32_f16 v[40:43], v[6:9], v[124:127], v[40:43]
	v_mfma_f32_16x16x32_f16 v[44:47], v[6:9], v[128:131], v[44:47]
	v_mfma_f32_16x16x32_f16 v[48:51], v[6:9], v[132:135], v[48:51]
	v_mfma_f32_16x16x32_f16 v[52:55], v[6:9], v[240:243], v[52:55]
	v_mfma_f32_16x16x32_f16 v[56:59], v[6:9], v[244:247], v[56:59]
	v_cvt_pk_f32_fp8_e32 v[10:11], v206
	v_cvt_pk_f32_fp8_sdwa v[12:13], v206 src0_sel:WORD_1
	v_cvt_pk_f32_fp8_e32 v[14:15], v207
	v_cvt_pk_f32_fp8_sdwa v[16:17], v207 src0_sel:WORD_1
	v_add_lshl_u32 v144, s48, v144, 8
	v_add_u32_e32 v144, v169, v144
	global_load_dwordx4 v[204:207], v144, s[86:87]
	v_cvt_pk_f32_fp8_e32 v[18:19], v210
	v_cvt_pk_f32_fp8_sdwa v[20:21], v210 src0_sel:WORD_1
	v_cvt_pk_f32_fp8_e32 v[108:109], v211
	v_cvt_pk_f32_fp8_sdwa v[110:111], v211 src0_sel:WORD_1
	v_add_lshl_u32 v145, s48, v145, 8
	v_add_u32_e32 v145, v169, v145
	global_load_dwordx4 v[208:211], v145, s[86:87]
	v_cvt_pk_f16_f32 v112, v10, v18
	v_cvt_pk_f16_f32 v116, v11, v19
	v_cvt_pk_f16_f32 v120, v12, v20
	v_cvt_pk_f16_f32 v124, v13, v21
	v_cvt_pk_f16_f32 v128, v14, v108
	v_cvt_pk_f16_f32 v132, v15, v109
	v_cvt_pk_f16_f32 v240, v16, v110
	v_cvt_pk_f16_f32 v244, v17, v111
	v_cvt_pk_f32_fp8_e32 v[10:11], v214
	v_cvt_pk_f32_fp8_sdwa v[12:13], v214 src0_sel:WORD_1
	v_cvt_pk_f32_fp8_e32 v[14:15], v215
	v_cvt_pk_f32_fp8_sdwa v[16:17], v215 src0_sel:WORD_1
	v_add_lshl_u32 v146, s48, v146, 8
	v_add_u32_e32 v146, v169, v146
	global_load_dwordx4 v[212:215], v146, s[86:87]
	v_cvt_pk_f32_fp8_e32 v[18:19], v218
	v_cvt_pk_f32_fp8_sdwa v[20:21], v218 src0_sel:WORD_1
	v_cvt_pk_f32_fp8_e32 v[108:109], v219
	v_cvt_pk_f32_fp8_sdwa v[110:111], v219 src0_sel:WORD_1
	v_add_lshl_u32 v147, s48, v147, 8
	v_add_u32_e32 v147, v169, v147
	global_load_dwordx4 v[216:219], v147, s[86:87]
	v_cvt_pk_f16_f32 v113, v10, v18
	v_cvt_pk_f16_f32 v117, v11, v19
	v_cvt_pk_f16_f32 v121, v12, v20
	v_cvt_pk_f16_f32 v125, v13, v21
	v_cvt_pk_f16_f32 v129, v14, v108
	v_cvt_pk_f16_f32 v133, v15, v109
	v_cvt_pk_f16_f32 v241, v16, v110
	v_cvt_pk_f16_f32 v245, v17, v111
	v_cvt_pk_f32_fp8_e32 v[10:11], v222
	v_cvt_pk_f32_fp8_sdwa v[12:13], v222 src0_sel:WORD_1
	v_cvt_pk_f32_fp8_e32 v[14:15], v223
	v_cvt_pk_f32_fp8_sdwa v[16:17], v223 src0_sel:WORD_1
	v_add_lshl_u32 v148, s48, v148, 8
	v_add_u32_e32 v148, v169, v148
	global_load_dwordx4 v[220:223], v148, s[86:87]
	v_cvt_pk_f32_fp8_e32 v[18:19], v226
	v_cvt_pk_f32_fp8_sdwa v[20:21], v226 src0_sel:WORD_1
	v_cvt_pk_f32_fp8_e32 v[108:109], v227
	v_cvt_pk_f32_fp8_sdwa v[110:111], v227 src0_sel:WORD_1
	v_add_lshl_u32 v149, s48, v149, 8
	v_add_u32_e32 v149, v169, v149
	global_load_dwordx4 v[224:227], v149, s[86:87]
	v_cvt_pk_f16_f32 v114, v10, v18
	v_cvt_pk_f16_f32 v118, v11, v19
	v_cvt_pk_f16_f32 v122, v12, v20
	v_cvt_pk_f16_f32 v126, v13, v21
	v_cvt_pk_f16_f32 v130, v14, v108
	v_cvt_pk_f16_f32 v134, v15, v109
	v_cvt_pk_f16_f32 v242, v16, v110
	v_cvt_pk_f16_f32 v246, v17, v111
	v_cvt_pk_f32_fp8_e32 v[10:11], v230
	v_cvt_pk_f32_fp8_sdwa v[12:13], v230 src0_sel:WORD_1
	v_cvt_pk_f32_fp8_e32 v[14:15], v231
	v_cvt_pk_f32_fp8_sdwa v[16:17], v231 src0_sel:WORD_1
	v_add_lshl_u32 v178, s48, v178, 8
	v_add_u32_e32 v178, v169, v178
	global_load_dwordx4 v[228:231], v178, s[86:87]
	v_cvt_pk_f32_fp8_e32 v[18:19], v234
	v_cvt_pk_f32_fp8_sdwa v[20:21], v234 src0_sel:WORD_1
	v_cvt_pk_f32_fp8_e32 v[108:109], v235
	v_cvt_pk_f32_fp8_sdwa v[110:111], v235 src0_sel:WORD_1
	v_add_lshl_u32 v179, s48, v179, 8
	v_add_u32_e32 v179, v169, v179
	global_load_dwordx4 v[232:235], v179, s[86:87]
	v_cvt_pk_f16_f32 v115, v10, v18
	v_cvt_pk_f16_f32 v119, v11, v19
	v_cvt_pk_f16_f32 v123, v12, v20
	v_cvt_pk_f16_f32 v127, v13, v21
	v_cvt_pk_f16_f32 v131, v14, v108
	v_cvt_pk_f16_f32 v135, v15, v109
	v_cvt_pk_f16_f32 v243, v16, v110
	v_cvt_pk_f16_f32 v247, v17, v111
	v_mfma_f32_16x16x32_f16 v[60:63], v[6:9], v[112:115], v[60:63]
	v_mfma_f32_16x16x32_f16 v[64:67], v[6:9], v[116:119], v[64:67]
	v_mfma_f32_16x16x32_f16 v[68:71], v[6:9], v[120:123], v[68:71]
	v_mfma_f32_16x16x32_f16 v[72:75], v[6:9], v[124:127], v[72:75]
	v_mfma_f32_16x16x32_f16 v[76:79], v[6:9], v[128:131], v[76:79]
	v_mfma_f32_16x16x32_f16 v[80:83], v[6:9], v[132:135], v[80:83]
	v_mfma_f32_16x16x32_f16 v[84:87], v[6:9], v[240:243], v[84:87]
	v_mfma_f32_16x16x32_f16 v[88:91], v[6:9], v[244:247], v[88:91]
	s_cmp_ge_i32 s12, s29
	s_cbranch_scc0 .LBB0_1472
	s_waitcnt vmcnt(0)
	s_branch .LBB0_1478

; #define LAS __attribute__((address_space(3)))
; __device__ __forceinline__ void dsa_unit(int wv, const Args& A, LAS unsigned char* lds, int s, int qt) {
;     ...
;         { const int ksub = lane >> 4, sl16 = lane & 15, g = sl16 >> 3;
;             float acc[4][16];
; #pragma unroll
;             for (int hh = 0; hh < 4; ++hh)
; #pragma unroll
;                 for (int d = 0; d < 16; ++d) acc[hh][d] = 0.f;
;             for (int eb = 0; eb < n; eb += 64) {
;                 h16x2 a2[4][8];
; #pragma unroll
;                 for (int hh = 0; hh < 4; ++hh)
; #pragma unroll
;                     for (int d2 = 0; d2 < 8; ++d2) a2[hh][d2] = (h16x2){0, 0};
; #pragma unroll
;                 for (int e0 = 0; e0 < 64; e0 += 4) { const int e = eb + e0 + ksub; const int j_ = lst[e];
;                     const unsigned char* vp = (s < 2) ? ws + WS_VC8 + ((size_t)s * SEQ + j_) * 256 : (j_ < PAST ? ws + WS_CV8 + ((size_t)(s - 2) * PAST + j_) * 256 : ws + WS_VC8 + ((size_t)NP + (s - 2) * 64 + (j_ - PAST)) * 256);
;                     const u32x4 wv8 = *(const u32x4*)(vp + sl16 * 16);
;                     const h16x4 ph = *(const LAS h16x4*)(Pw + e * 8 + g * 4);
;                     h16x2 v2[8];
; #pragma unroll
;                     for (int d2 = 0; d2 < 8; ++d2) { const f32x2 f2 = (d2 & 1) ? __builtin_amdgcn_cvt_pk_f32_fp8((int)wv8[d2 >> 1], true) : __builtin_amdgcn_cvt_pk_f32_fp8((int)wv8[d2 >> 1], false);
;                         v2[d2] = (h16x2){(h16)f2[0], (h16)f2[1]}; }
; #pragma unroll
;                     for (int hh = 0; hh < 4; ++hh) { const h16x2 pp = {ph[hh], ph[hh]};
; #pragma unroll
;                         for (int d2 = 0; d2 < 8; ++d2) a2[hh][d2] = __builtin_elementwise_fma(pp, v2[d2], a2[hh][d2]); } }
; #pragma unroll
;                 for (int hh = 0; hh < 4; ++hh)
; #pragma unroll
;                     for (int d2 = 0; d2 < 8; ++d2) { acc[hh][2 * d2] += (float)a2[hh][d2][0]; acc[hh][2 * d2 + 1] += (float)a2[hh][d2][1]; }
;             }
; #pragma unroll
;             for (int hh = 0; hh < 4; ++hh) { h16x8 o8a, o8b;
; #pragma unroll
;                 for (int d = 0; d < 16; ++d) { float t = acc[hh][d] + __shfl_xor(acc[hh][d], 16); t += __shfl_xor(t, 32); if (d < 8) o8a[d] = (h16)t; else o8b[d - 8] = (h16)t; }
.LBB0_1477:
	v_mov_b32_e32 v28, 0
	v_mov_b32_e32 v29, 0
	v_mov_b32_e32 v30, 0
	v_mov_b32_e32 v31, 0
	v_mov_b32_e32 v32, 0
	v_mov_b32_e32 v33, 0
	v_mov_b32_e32 v34, 0
	v_mov_b32_e32 v35, 0
	v_mov_b32_e32 v36, 0
	v_mov_b32_e32 v37, 0
	v_mov_b32_e32 v38, 0
	v_mov_b32_e32 v39, 0
	v_mov_b32_e32 v40, 0
	v_mov_b32_e32 v41, 0
	v_mov_b32_e32 v42, 0
	v_mov_b32_e32 v43, 0
	v_mov_b32_e32 v44, 0
	v_mov_b32_e32 v45, 0
	v_mov_b32_e32 v46, 0
	v_mov_b32_e32 v47, 0
	v_mov_b32_e32 v48, 0
	v_mov_b32_e32 v49, 0
	v_mov_b32_e32 v50, 0
	v_mov_b32_e32 v51, 0
	v_mov_b32_e32 v52, 0
	v_mov_b32_e32 v53, 0
	v_mov_b32_e32 v54, 0
	v_mov_b32_e32 v55, 0
	v_mov_b32_e32 v56, 0
	v_mov_b32_e32 v57, 0
	v_mov_b32_e32 v58, 0
	v_mov_b32_e32 v59, 0
	v_mov_b32_e32 v60, 0
	v_mov_b32_e32 v61, 0
	v_mov_b32_e32 v62, 0
	v_mov_b32_e32 v63, 0
	v_mov_b32_e32 v64, 0
	v_mov_b32_e32 v65, 0
	v_mov_b32_e32 v66, 0
	v_mov_b32_e32 v67, 0
	v_mov_b32_e32 v68, 0
	v_mov_b32_e32 v69, 0
	v_mov_b32_e32 v70, 0
	v_mov_b32_e32 v71, 0
	v_mov_b32_e32 v72, 0
	v_mov_b32_e32 v73, 0
	v_mov_b32_e32 v74, 0
	v_mov_b32_e32 v75, 0
	v_mov_b32_e32 v76, 0
	v_mov_b32_e32 v77, 0
	v_mov_b32_e32 v78, 0
	v_mov_b32_e32 v79, 0
	v_mov_b32_e32 v80, 0
	v_mov_b32_e32 v81, 0
	v_mov_b32_e32 v82, 0
	v_mov_b32_e32 v83, 0
	v_mov_b32_e32 v84, 0
	v_mov_b32_e32 v85, 0
	v_mov_b32_e32 v86, 0
	v_mov_b32_e32 v87, 0
	v_mov_b32_e32 v88, 0
	v_mov_b32_e32 v89, 0
	v_mov_b32_e32 v90, 0
	v_mov_b32_e32 v91, 0
.LBB0_1478:
	s_nop 7
	v_mbcnt_lo_u32_b32 v0, -1, 0
	v_mbcnt_hi_u32_b32 v0, -1, v0
	v_lshrrev_b32_e32 v93, 4, v0
	v_bfe_u32 v0, v0, 3, 1
	s_lshl_b64 s[0:1], s[22:23], 12
	s_xor_b64 s[12:13], s[24:25], -1
	v_cmp_eq_u32_e32 vcc, v93, v0
	v_lshl_add_u64 v[10:11], v[26:27], 0, s[0:1]
	v_lshlrev_b32_e32 v0, 1, v24
	v_lshl_add_u64 v[10:11], v[10:11], 0, v[0:1]
	s_and_saveexec_b64 s[14:15], vcc
	s_cbranch_execz .LBB0_1428
	v_cvt_pk_f16_f32 v112, v28, v32
	v_cvt_pk_f16_f32 v113, v36, v40
	v_cvt_pk_f16_f32 v114, v44, v48
	v_cvt_pk_f16_f32 v115, v52, v56
	v_cvt_pk_f16_f32 v116, v60, v64
	v_cvt_pk_f16_f32 v117, v68, v72
	v_cvt_pk_f16_f32 v118, v76, v80
	v_cvt_pk_f16_f32 v119, v84, v88
	global_store_dwordx4 v[10:11], v[112:115], off
	global_store_dwordx4 v[10:11], v[116:119], off offset:16
	v_cvt_pk_f16_f32 v120, v29, v33
	v_cvt_pk_f16_f32 v121, v37, v41
	v_cvt_pk_f16_f32 v122, v45, v49
	v_cvt_pk_f16_f32 v123, v53, v57
	v_cvt_pk_f16_f32 v124, v61, v65
	v_cvt_pk_f16_f32 v125, v69, v73
	v_cvt_pk_f16_f32 v126, v77, v81
	v_cvt_pk_f16_f32 v127, v85, v89
	global_store_dwordx4 v[10:11], v[120:123], off offset:256
	global_store_dwordx4 v[10:11], v[124:127], off offset:272
	v_cvt_pk_f16_f32 v112, v30, v34
	v_cvt_pk_f16_f32 v113, v38, v42
	v_cvt_pk_f16_f32 v114, v46, v50
	v_cvt_pk_f16_f32 v115, v54, v58
	v_cvt_pk_f16_f32 v116, v62, v66
	v_cvt_pk_f16_f32 v117, v70, v74
	v_cvt_pk_f16_f32 v118, v78, v82
	v_cvt_pk_f16_f32 v119, v86, v90
	global_store_dwordx4 v[10:11], v[112:115], off offset:512
	global_store_dwordx4 v[10:11], v[116:119], off offset:528
	v_cvt_pk_f16_f32 v120, v31, v35
	v_cvt_pk_f16_f32 v121, v39, v43
	v_cvt_pk_f16_f32 v122, v47, v51
	v_cvt_pk_f16_f32 v123, v55, v59
	v_cvt_pk_f16_f32 v124, v63, v67
	v_cvt_pk_f16_f32 v125, v71, v75
	v_cvt_pk_f16_f32 v126, v79, v83
	v_cvt_pk_f16_f32 v127, v87, v91
	global_store_dwordx4 v[10:11], v[120:123], off offset:768
	global_store_dwordx4 v[10:11], v[124:127], off offset:784
	s_branch .LBB0_1428
